# WKV loader half: per-chunk operand loads via one running byte offset with SGPR bases and a running v pointer (no per-chunk 64-bit address rebuild / SGPR reloads)
# speedup vs baseline: 1.0596x; 1.0021x over previous
.LBB0_182:
	s_or_b64 exec, exec, s[20:21]
	v_readlane_b32 s4, v251, 14
	s_mul_i32 s2, s28, 0x1800000
	v_readlane_b32 s6, v251, 16
	v_readlane_b32 s5, v251, 15
	v_readlane_b32 s7, v251, 17
	v_readlane_b32 s8, v251, 18
	v_readlane_b32 s9, v251, 19
	v_readlane_b32 s10, v251, 20
	v_readlane_b32 s11, v251, 21
	v_readlane_b32 s12, v251, 22
	v_readlane_b32 s13, v251, 23
	v_readlane_b32 s14, v251, 24
	v_readlane_b32 s15, v251, 25
	v_readlane_b32 s16, v251, 26
	v_readlane_b32 s17, v251, 27
	v_readlane_b32 s18, v251, 28
	v_readlane_b32 s19, v251, 29
	s_add_u32 s2, s6, s2
	s_addc_u32 s3, s7, 0
	v_readlane_b32 s4, v252, 48
	v_lshlrev_b64 v[54:55], 2, v[92:93]
	v_readlane_b32 s10, v252, 54
	v_readlane_b32 s11, v252, 55
	v_lshl_add_u64 v[56:57], s[2:3], 0, v[54:55]
	s_cmp_eq_u32 s28, 0
	v_lshl_add_u64 v[54:55], s[10:11], 0, v[54:55]
	v_lshlrev_b32_e32 v62, 2, v90
	v_mov_b32_e32 v63, v1
	v_lshl_add_u64 v[54:55], v[60:61], 2, v[54:55]
	v_mov_b32_e32 v59, v1
	s_mov_b32 s79, 0
	s_cselect_b64 vcc, -1, 0
	v_lshl_add_u64 v[94:95], v[56:57], 0, v[62:63]
	v_or_b32_e32 v0, v0, v108
	v_lshl_add_u64 v[96:97], v[54:55], 0, v[58:59]
	s_waitcnt lgkmcnt(0)
	s_barrier
	v_readlane_b32 s5, v252, 49
	v_readlane_b32 s6, v252, 50
	v_readlane_b32 s7, v252, 51
	v_readlane_b32 s8, v252, 52
	v_readlane_b32 s9, v252, 53
	v_readlane_b32 s12, v252, 56
	v_readlane_b32 s13, v252, 57
	v_readlane_b32 s14, v252, 58
	v_readlane_b32 s15, v252, 59
	v_readlane_b32 s16, v252, 60
	v_readlane_b32 s17, v252, 61
	v_readlane_b32 s18, v252, 62
	v_readlane_b32 s19, v252, 63
	s_mov_b32 s60, 0x8000
	s_mov_b32 s61, 0
	s_cmp_lg_u64 vcc, 0
	s_cbranch_scc1 .Lwkvl_fw
	s_mov_b32 s60, 0xffff8000
	s_mov_b32 s61, -1
.Lwkvl_fw:
	v_readlane_b32 s62, v252, 52
	v_readlane_b32 s63, v252, 53
	v_readlane_b32 s64, v252, 50
	v_readlane_b32 s65, v252, 51
	v_add_u32_e32 v87, 32, v185
	v_sub_u32_e32 v91, 0xfff, v87
	v_cndmask_b32_e32 v87, v91, v87, vcc
	v_add_u32_e32 v87, s78, v87
	v_lshlrev_b32_e32 v87, 11, v87
	v_lshl_add_u32 v86, v0, 2, v87
	v_add_u32_e32 v87, 32, v205
	v_sub_u32_e32 v91, 0xfff, v87
	v_cndmask_b32_e32 v87, v91, v87, vcc
	v_add_u32_e32 v87, s78, v87
	v_lshlrev_b32_e32 v88, 11, v87
	v_mov_b32_e32 v89, v1
	v_lshl_add_u64 v[88:89], v[96:97], 0, v[88:89]
	s_branch .LBB0_185

.LBB0_197:
	s_or_b64 exec, exec, s[76:77]
	s_cmpk_gt_u32 s79, 0xfc
	s_cbranch_scc1 .LBB0_199
	v_add_u32_e32 v86, s60, v86
	v_lshl_add_u64 v[88:89], v[88:89], 0, s[60:61]
	global_load_dwordx4 v[2:5], v86, s[54:55]
	global_load_dwordx4 v[6:9], v86, s[62:63]
	global_load_dwordx4 v[10:13], v86, s[58:59]
	global_load_dwordx4 v[14:17], v86, s[56:57]
	global_load_dwordx4 v[18:21], v86, s[64:65]
	global_load_dwordx4 v[34:37], v[88:89], off

.LBB0_218:
	v_add_u32_e32 v86, s60, v86
	v_lshl_add_u64 v[88:89], v[88:89], 0, s[60:61]
	global_load_dwordx4 v[22:25], v86, s[54:55]
	global_load_dwordx4 v[26:29], v86, s[62:63]
	global_load_dwordx4 v[30:33], v86, s[58:59]
	global_load_dwordx4 v[38:41], v86, s[56:57]
	global_load_dwordx4 v[42:45], v86, s[64:65]
	global_load_dwordx4 v[46:49], v[88:89], off
	s_and_saveexec_b64 s[76:77], s[44:45]
	s_cbranch_execz .LBB0_183
